# P6 tiles from a device-wide counter (first workgroup out of P5 takes the first row block's tile): index fetched by thread 0 after P5, published through the LDS word, flag poll on the fetched tile's ro
# baseline (speedup 1.0000x reference)
.LBB0_3:
	s_or_b64 exec, exec, s[2:3]
	v_cmp_eq_u32_e32 vcc, 0, v0
	s_and_saveexec_b64 s[2:3], vcc
	s_cbranch_execz .Lq5_init_done
	v_mov_b32_e32 v4, s94
	v_mov_b32_e32 v5, s95
	v_add_co_u32_e32 v4, vcc, 0x3020, v4
	s_nop 1
	v_addc_co_u32_e32 v5, vcc, 0, v5, vcc
	v_mov_b32_e32 v6, 0x100
	global_atomic_swap v[4:5], v6, off
	v_add_co_u32_e32 v4, vcc, 16, v4
	s_nop 1
	v_addc_co_u32_e32 v5, vcc, 0, v5, vcc
	v_mov_b32_e32 v6, 0
	global_atomic_swap v[4:5], v6, off

.Lp6_poll_setup:
	s_add_u32 s0, s94, 0x3030
	s_addc_u32 s1, s95, 0
	v_mov_b32_e32 v1, 0
	v_mov_b32_e32 v2, 1
	global_atomic_add v3, v1, v2, s[0:1] sc0
	s_waitcnt vmcnt(0)
	v_readfirstlane_b32 s98, v3
	v_mov_b32_e32 v4, 0x20600
	ds_write_b32 v4, v3
	s_nop 1
	s_ashr_i32 s0, s98, 2
	s_lshl_b32 s0, s0, 6
	s_add_u32 s6, s94, s0
	s_addc_u32 s7, s95, 0
	s_add_u32 s6, s6, 0x3000
	s_addc_u32 s7, s7, 0
	s_mov_b32 s11, 0x400001
	v_mov_b32_e32 v1, 0
.Lp6_flag_poll:
	global_load_dword v2, v1, s[6:7] sc1
	s_waitcnt vmcnt(0)
	v_cmp_lt_u32_e32 vcc, 21, v2
	s_cbranch_vccnz .LBB0_389
	s_sleep 8
	s_add_i32 s11, s11, -1
	s_cmp_lg_u32 s11, 0
	s_cbranch_scc1 .Lp6_flag_poll
.LBB0_389:
	s_waitcnt lgkmcnt(0)
	buffer_inv sc1
	s_waitcnt vmcnt(0)
.LBB0_390:
	s_or_b64 exec, exec, s[4:5]
	s_barrier
	v_mov_b32_e32 v1, 0x20600
	ds_read_b32 v1, v1
	s_waitcnt lgkmcnt(0)
	v_readfirstlane_b32 s10, v1
	s_nop 3
